# v49 + P4a forget-bias loads hoisted to chunk-loop top
# baseline (speedup 1.0000x reference)
.LBB0_351:
	global_load_dword v100, v1, s[42:43]
	global_load_dword v101, v1, s[42:43] offset:4
	v_add_u32_e32 v10, s15, v171
	v_add_u32_e32 v34, 16, v10
	v_add_u32_e32 v38, 32, v10
	v_ashrrev_i32_e32 v11, 31, v10
	v_ashrrev_i32_e32 v35, 31, v34
	v_ashrrev_i32_e32 v39, 31, v38
	v_lshlrev_b64 v[50:51], 11, v[10:11]
	v_lshlrev_b64 v[54:55], 11, v[34:35]
	v_lshlrev_b64 v[58:59], 11, v[38:39]
	v_lshl_add_u64 v[30:31], v[4:5], 0, v[50:51]
	v_lshl_add_u64 v[34:35], v[4:5], 0, v[54:55]
	v_lshl_add_u64 v[38:39], v[4:5], 0, v[58:59]
	global_load_dwordx4 v[26:29], v[2:3], off
	v_add_u32_e32 v10, 48, v10
	global_load_dwordx4 v[30:33], v[30:31], off
	v_ashrrev_i32_e32 v11, 31, v10
	global_load_dwordx4 v[34:37], v[34:35], off
	v_lshlrev_b64 v[10:11], 11, v[10:11]
	global_load_dwordx4 v[38:41], v[38:39], off
	v_lshl_add_u64 v[42:43], v[4:5], 0, v[10:11]
	global_load_dwordx4 v[42:45], v[42:43], off
	s_nop 0
	global_load_dwordx4 v[46:49], v[2:3], off offset:64
	v_lshl_add_u64 v[66:67], s[36:37], 0, v[50:51]
	v_lshl_add_u64 v[68:69], s[36:37], 0, v[54:55]
	v_lshl_add_u64 v[50:51], v[66:67], 0, v[0:1]
	v_lshl_add_u64 v[54:55], v[68:69], 0, v[0:1]
	v_lshl_add_u64 v[70:71], s[36:37], 0, v[58:59]
	global_load_dwordx4 v[50:53], v[50:51], off
	v_lshl_add_u64 v[58:59], v[70:71], 0, v[0:1]
	global_load_dwordx4 v[54:57], v[54:55], off
	v_lshl_add_u64 v[10:11], s[36:37], 0, v[10:11]
	global_load_dwordx4 v[58:61], v[58:59], off
	v_lshl_add_u64 v[62:63], v[10:11], 0, v[0:1]
	v_lshl_add_u64 v[72:73], v[68:69], 0, v[6:7]
	s_waitcnt vmcnt(7)
	v_mfma_f32_16x16x32_bf16 v[30:33], v[30:33], v[26:29], 0
	s_waitcnt vmcnt(6)
	v_mfma_f32_16x16x32_bf16 v[34:37], v[34:37], v[26:29], 0
	s_waitcnt vmcnt(5)
	v_mfma_f32_16x16x32_bf16 v[38:41], v[38:41], v[26:29], 0
	s_waitcnt vmcnt(4)
	v_mfma_f32_16x16x32_bf16 v[26:29], v[42:45], v[26:29], 0
	global_load_dwordx4 v[42:45], v[62:63], off
	v_lshl_add_u64 v[62:63], v[66:67], 0, v[6:7]
	v_lshl_add_u64 v[66:67], v[66:67], 0, v[8:9]
	s_waitcnt vmcnt(3)
	v_mfma_f32_16x16x32_bf16 v[30:33], v[50:53], v[46:49], v[30:33]
	global_load_dwordx4 v[50:53], v[62:63], off
	s_nop 0
	global_load_dwordx4 v[62:65], v[2:3], off offset:128
	s_waitcnt vmcnt(4)
	v_mfma_f32_16x16x32_bf16 v[34:37], v[54:57], v[46:49], v[34:37]
	global_load_dwordx4 v[54:57], v[72:73], off
	v_lshl_add_u64 v[72:73], v[70:71], 0, v[6:7]
	s_waitcnt vmcnt(4)
	v_mfma_f32_16x16x32_bf16 v[38:41], v[58:61], v[46:49], v[38:41]
	global_load_dwordx4 v[58:61], v[72:73], off
	v_lshl_add_u64 v[72:73], v[10:11], 0, v[6:7]
	v_lshl_add_u64 v[10:11], v[10:11], 0, v[8:9]
	s_waitcnt vmcnt(2)
	v_mfma_f32_16x16x32_bf16 v[30:33], v[50:53], v[62:65], v[30:33]
	v_mfma_f32_16x16x32_bf16 v[26:29], v[42:45], v[46:49], v[26:29]
	global_load_dwordx4 v[42:45], v[72:73], off
	global_load_dwordx4 v[46:49], v[2:3], off offset:192
	global_load_dwordx4 v[50:53], v[66:67], off
	s_waitcnt vmcnt(4)
	v_mfma_f32_16x16x32_bf16 v[34:37], v[54:57], v[62:65], v[34:37]
	s_waitcnt vmcnt(3)
	v_mfma_f32_16x16x32_bf16 v[38:41], v[58:61], v[62:65], v[38:41]
	s_waitcnt vmcnt(2)
	v_mfma_f32_16x16x32_bf16 v[26:29], v[42:45], v[62:65], v[26:29]
	global_load_dwordx4 v[42:45], v[10:11], off
	v_lshl_add_u64 v[66:67], v[68:69], 0, v[8:9]
	global_load_dwordx4 v[54:57], v[66:67], off
	v_lshl_add_u64 v[66:67], v[70:71], 0, v[8:9]
	global_load_dwordx4 v[58:61], v[66:67], off
	v_add_u32_e32 v10, s15, v204
	v_ashrrev_i32_e32 v11, 31, v10
	s_waitcnt vmcnt(3)
	v_mfma_f32_16x16x32_bf16 v[30:33], v[50:53], v[46:49], v[30:33]
	v_lshlrev_b64 v[50:51], 6, v[10:11]
	v_lshl_add_u64 v[66:67], s[60:61], 0, v[50:51]
	global_load_dwordx4 v[50:53], v[66:67], off
	v_lshl_add_u64 v[10:11], v[10:11], 2, s[38:39]
	s_waitcnt vmcnt(3)
	v_mfma_f32_16x16x32_bf16 v[26:29], v[42:45], v[46:49], v[26:29]
	s_waitcnt vmcnt(0)
	v_add_f32_e32 v25, v50, v51
	v_mfma_f32_16x16x32_bf16 v[34:37], v[54:57], v[46:49], v[34:37]
	global_load_dwordx4 v[54:57], v[66:67], off offset:16
	global_load_dwordx4 v[62:65], v[66:67], off offset:32
	v_mfma_f32_16x16x32_bf16 v[38:41], v[58:61], v[46:49], v[38:41]
	global_load_dwordx4 v[58:61], v[66:67], off offset:48
	ds_write2_b32 v19, v30, v31 offset1:16
	ds_write2_b32 v19, v32, v33 offset0:32 offset1:48
	s_nop 1
	ds_write2_b32 v22, v34, v35 offset1:16
	ds_write2_b32 v22, v36, v37 offset0:32 offset1:48
	s_nop 0
	ds_write2_b32 v23, v38, v39 offset1:16
	ds_write2_b32 v23, v40, v41 offset0:32 offset1:48
	ds_write2_b32 v24, v26, v27 offset1:16
	ds_write2_b32 v24, v28, v29 offset0:32 offset1:48
	s_waitcnt lgkmcnt(0)
	s_barrier
	v_mov_b32_e32 v34, v100
	v_add_f32_e32 v26, v52, v53
	v_add_f32_e32 v25, v25, v26
	s_waitcnt vmcnt(2)
	v_add_f32_e32 v27, v54, v55
	v_add_f32_e32 v28, v56, v57
	s_waitcnt vmcnt(1)
	v_add_f32_e32 v29, v62, v63
	v_add_f32_e32 v30, v64, v65
	v_add_f32_e32 v26, v27, v28
	s_waitcnt vmcnt(0)
	v_add_f32_e32 v31, v58, v59
	v_add_f32_e32 v32, v60, v61
	v_add_f32_e32 v27, v29, v30
	v_add_f32_e32 v25, v25, v26
	v_add_f32_e32 v28, v31, v32
	v_add_f32_e32 v25, v25, v27
	v_add_f32_e32 v25, v25, v28
	v_fmamk_f32 v25, v25, 0x3a800000, v20
	v_mul_f32_e32 v26, 0x4f800000, v25
	v_cmp_gt_f32_e32 vcc, s57, v25
	s_nop 1
	v_cndmask_b32_e32 v25, v25, v26, vcc
	v_sqrt_f32_e32 v26, v25
	s_nop 0
	v_add_u32_e32 v27, -1, v26
	v_add_u32_e32 v28, 1, v26
	v_fma_f32 v29, -v27, v26, v25
	v_fma_f32 v30, -v28, v26, v25
	v_cmp_ge_f32_e64 s[22:23], 0, v29
	s_nop 1
	v_cndmask_b32_e64 v26, v26, v27, s[22:23]
	v_cmp_lt_f32_e64 s[22:23], 0, v30
	s_nop 1
	v_cndmask_b32_e64 v26, v26, v28, s[22:23]
	v_mul_f32_e32 v27, 0x37800000, v26
	v_cndmask_b32_e32 v26, v26, v27, vcc
	v_cmp_class_f32_e32 vcc, v25, v21
	s_nop 1
	v_cndmask_b32_e32 v25, v26, v25, vcc
	v_div_scale_f32 v35, s[22:23], v25, v25, 1.0
	v_rcp_f32_e32 v37, v35
	ds_read2st64_b32 v[26:27], v12 offset1:16
	ds_read2st64_b32 v[28:29], v12 offset0:32 offset1:48
	ds_read2st64_b32 v[30:31], v12 offset0:64 offset1:80
	ds_read2st64_b32 v[32:33], v12 offset0:96 offset1:112
	v_div_scale_f32 v36, vcc, 1.0, v25, 1.0
	v_fma_f32 v38, -v35, v37, 1.0
	s_waitcnt lgkmcnt(3)
	v_add_f32_e32 v26, 0, v26
	v_fmac_f32_e32 v37, v38, v37
	v_add_f32_e32 v26, v26, v27
	v_mul_f32_e32 v38, v36, v37
	s_waitcnt lgkmcnt(2)
	v_add_f32_e32 v26, v26, v28
	v_fma_f32 v39, -v35, v38, v36
	v_add_f32_e32 v26, v26, v29
	v_fmac_f32_e32 v38, v39, v37
	s_waitcnt lgkmcnt(1)
	v_add_f32_e32 v26, v26, v30
	v_fma_f32 v27, -v35, v38, v36
	v_add_f32_e32 v26, v26, v31
	v_div_fmas_f32 v27, v27, v37, v38
	s_waitcnt lgkmcnt(0)
	v_add_f32_e32 v26, v26, v32
	v_div_fixup_f32 v25, v27, v25, 1.0
	v_add_f32_e32 v26, v26, v33
	s_waitcnt vmcnt(0)
	v_fmac_f32_e32 v34, v25, v26
	v_mul_f32_e64 v26, |v34|, s64
	v_exp_f32_e32 v26, v26
	v_min_f32_e32 v27, 0, v34
	v_lshl_add_u64 v[28:29], v[10:11], 0, s[46:47]
	v_add_f32_e32 v26, 1.0, v26
	v_log_f32_e32 v26, v26
	s_nop 0
	v_fmac_f32_e32 v27, 0xbf317218, v26
	ds_bpermute_b32 v26, v13, v27
	s_waitcnt lgkmcnt(0)
	v_add_f32_e32 v26, v27, v26
	v_cndmask_b32_e64 v26, v26, v27, s[8:9]
	ds_bpermute_b32 v27, v14, v26
	s_waitcnt lgkmcnt(0)
	v_add_f32_e32 v27, v26, v27
	v_cndmask_b32_e64 v26, v27, v26, s[10:11]
	ds_bpermute_b32 v27, v15, v26
	s_waitcnt lgkmcnt(0)
	v_add_f32_e32 v27, v26, v27
	v_cndmask_b32_e64 v26, v27, v26, s[12:13]
	ds_bpermute_b32 v27, v16, v26
	s_waitcnt lgkmcnt(0)
	v_add_f32_e32 v27, v26, v27
	v_cndmask_b32_e64 v26, v27, v26, s[16:17]
	ds_bpermute_b32 v27, v17, v26
	s_waitcnt lgkmcnt(0)
	v_add_f32_e32 v27, v26, v27
	v_cndmask_b32_e64 v27, v27, v26, s[18:19]
	ds_bpermute_b32 v26, v18, v27
	s_waitcnt lgkmcnt(0)
	v_add_f32_e32 v26, v27, v26
	v_cndmask_b32_e64 v27, v26, v27, s[20:21]
	global_store_dword v[28:29], v27, off sc1
	s_and_saveexec_b64 s[22:23], s[0:1]
	s_cbranch_execz .LBB0_353
	s_add_i32 s44, s14, s65
	s_ashr_i32 s45, s44, 31
	s_lshl_b64 s[44:45], s[44:45], 2
	s_add_u32 s44, s74, s44
	s_addc_u32 s45, s75, s45
	global_store_dword v1, v26, s[44:45] sc1
.LBB0_353:
	s_or_b64 exec, exec, s[22:23]
	v_mov_b32_e32 v34, v101
	v_add_u32_e32 v32, 4, v12
	ds_read2st64_b32 v[26:27], v32 offset1:16
	ds_read2st64_b32 v[28:29], v32 offset0:32 offset1:48
	ds_read2st64_b32 v[30:31], v32 offset0:64 offset1:80
	ds_read2st64_b32 v[32:33], v32 offset0:96 offset1:112
	v_lshl_add_u64 v[10:11], v[10:11], 0, s[48:49]
	s_waitcnt lgkmcnt(3)
	v_add_f32_e32 v26, 0, v26
	v_add_f32_e32 v26, v26, v27
	s_waitcnt lgkmcnt(2)
	v_add_f32_e32 v26, v26, v28
	v_add_f32_e32 v26, v26, v29
	s_waitcnt lgkmcnt(1)
	v_add_f32_e32 v26, v26, v30
	v_add_f32_e32 v26, v26, v31
	s_waitcnt lgkmcnt(0)
	v_add_f32_e32 v26, v26, v32
	v_add_f32_e32 v26, v26, v33
	v_fmac_f32_e32 v34, v25, v26
	v_mul_f32_e64 v25, |v34|, s64
	v_exp_f32_e32 v25, v25
	v_min_f32_e32 v26, 0, v34
	v_add_f32_e32 v25, 1.0, v25
	v_log_f32_e32 v25, v25
	s_nop 0
	v_fmac_f32_e32 v26, 0xbf317218, v25
	ds_bpermute_b32 v25, v13, v26
	s_waitcnt lgkmcnt(0)
	v_add_f32_e32 v25, v26, v25
	v_cndmask_b32_e64 v25, v25, v26, s[8:9]
	ds_bpermute_b32 v26, v14, v25
	s_waitcnt lgkmcnt(0)
	v_add_f32_e32 v26, v25, v26
	v_cndmask_b32_e64 v25, v26, v25, s[10:11]
	ds_bpermute_b32 v26, v15, v25
	s_waitcnt lgkmcnt(0)
	v_add_f32_e32 v26, v25, v26
	v_cndmask_b32_e64 v25, v26, v25, s[12:13]
	ds_bpermute_b32 v26, v16, v25
	s_waitcnt lgkmcnt(0)
	v_add_f32_e32 v26, v25, v26
	v_cndmask_b32_e64 v25, v26, v25, s[16:17]
	ds_bpermute_b32 v26, v17, v25
	s_waitcnt lgkmcnt(0)
	v_add_f32_e32 v26, v25, v26
	v_cndmask_b32_e64 v26, v26, v25, s[18:19]
	ds_bpermute_b32 v25, v18, v26
	s_waitcnt lgkmcnt(0)
	v_add_f32_e32 v25, v26, v25
	v_cndmask_b32_e64 v26, v25, v26, s[20:21]
	global_store_dword v[10:11], v26, off sc1
	s_and_saveexec_b64 s[22:23], s[0:1]
	s_cbranch_execz .LBB0_350
	s_add_i32 s33, s14, s65
	s_add_i32 s44, s33, 0x100
	s_ashr_i32 s45, s44, 31
	s_lshl_b64 s[44:45], s[44:45], 2
	s_add_u32 s44, s74, s44
	s_addc_u32 s45, s75, s45
	global_store_dword v1, v25, s[44:45] sc1
	s_branch .LBB0_350

.LBB0_443:
	global_load_dword v100, v1, s[40:41]
	global_load_dword v101, v1, s[40:41] offset:4
	v_add_u32_e32 v10, s15, v171
	v_add_u32_e32 v34, 16, v10
	v_add_u32_e32 v38, 32, v10
	v_ashrrev_i32_e32 v11, 31, v10
	v_ashrrev_i32_e32 v35, 31, v34
	v_ashrrev_i32_e32 v39, 31, v38
	v_lshlrev_b64 v[50:51], 11, v[10:11]
	v_lshlrev_b64 v[54:55], 11, v[34:35]
	v_lshlrev_b64 v[58:59], 11, v[38:39]
	v_lshl_add_u64 v[30:31], v[4:5], 0, v[50:51]
	v_lshl_add_u64 v[34:35], v[4:5], 0, v[54:55]
	v_lshl_add_u64 v[38:39], v[4:5], 0, v[58:59]
	global_load_dwordx4 v[26:29], v[2:3], off
	v_add_u32_e32 v10, 48, v10
	global_load_dwordx4 v[30:33], v[30:31], off
	v_ashrrev_i32_e32 v11, 31, v10
	global_load_dwordx4 v[34:37], v[34:35], off
	v_lshlrev_b64 v[10:11], 11, v[10:11]
	global_load_dwordx4 v[38:41], v[38:39], off
	v_lshl_add_u64 v[42:43], v[4:5], 0, v[10:11]
	global_load_dwordx4 v[42:45], v[42:43], off
	s_nop 0
	global_load_dwordx4 v[46:49], v[2:3], off offset:64
	v_lshl_add_u64 v[66:67], s[36:37], 0, v[50:51]
	v_lshl_add_u64 v[68:69], s[36:37], 0, v[54:55]
	v_lshl_add_u64 v[50:51], v[66:67], 0, v[0:1]
	v_lshl_add_u64 v[54:55], v[68:69], 0, v[0:1]
	v_lshl_add_u64 v[70:71], s[36:37], 0, v[58:59]
	global_load_dwordx4 v[50:53], v[50:51], off
	v_lshl_add_u64 v[58:59], v[70:71], 0, v[0:1]
	global_load_dwordx4 v[54:57], v[54:55], off
	v_lshl_add_u64 v[10:11], s[36:37], 0, v[10:11]
	global_load_dwordx4 v[58:61], v[58:59], off
	v_lshl_add_u64 v[62:63], v[10:11], 0, v[0:1]
	v_lshl_add_u64 v[72:73], v[68:69], 0, v[6:7]
	s_waitcnt vmcnt(7)
	v_mfma_f32_16x16x32_bf16 v[30:33], v[30:33], v[26:29], 0
	s_waitcnt vmcnt(6)
	v_mfma_f32_16x16x32_bf16 v[34:37], v[34:37], v[26:29], 0
	s_waitcnt vmcnt(5)
	v_mfma_f32_16x16x32_bf16 v[38:41], v[38:41], v[26:29], 0
	s_waitcnt vmcnt(4)
	v_mfma_f32_16x16x32_bf16 v[26:29], v[42:45], v[26:29], 0
	global_load_dwordx4 v[42:45], v[62:63], off
	v_lshl_add_u64 v[62:63], v[66:67], 0, v[6:7]
	v_lshl_add_u64 v[66:67], v[66:67], 0, v[8:9]
	s_waitcnt vmcnt(3)
	v_mfma_f32_16x16x32_bf16 v[30:33], v[50:53], v[46:49], v[30:33]
	global_load_dwordx4 v[50:53], v[62:63], off
	s_nop 0
	global_load_dwordx4 v[62:65], v[2:3], off offset:128
	s_waitcnt vmcnt(4)
	v_mfma_f32_16x16x32_bf16 v[34:37], v[54:57], v[46:49], v[34:37]
	global_load_dwordx4 v[54:57], v[72:73], off
	v_lshl_add_u64 v[72:73], v[70:71], 0, v[6:7]
	s_waitcnt vmcnt(4)
	v_mfma_f32_16x16x32_bf16 v[38:41], v[58:61], v[46:49], v[38:41]
	global_load_dwordx4 v[58:61], v[72:73], off
	v_lshl_add_u64 v[72:73], v[10:11], 0, v[6:7]
	v_lshl_add_u64 v[10:11], v[10:11], 0, v[8:9]
	s_waitcnt vmcnt(2)
	v_mfma_f32_16x16x32_bf16 v[30:33], v[50:53], v[62:65], v[30:33]
	v_mfma_f32_16x16x32_bf16 v[26:29], v[42:45], v[46:49], v[26:29]
	global_load_dwordx4 v[42:45], v[72:73], off
	global_load_dwordx4 v[46:49], v[2:3], off offset:192
	global_load_dwordx4 v[50:53], v[66:67], off
	s_waitcnt vmcnt(4)
	v_mfma_f32_16x16x32_bf16 v[34:37], v[54:57], v[62:65], v[34:37]
	s_waitcnt vmcnt(3)
	v_mfma_f32_16x16x32_bf16 v[38:41], v[58:61], v[62:65], v[38:41]
	s_waitcnt vmcnt(2)
	v_mfma_f32_16x16x32_bf16 v[26:29], v[42:45], v[62:65], v[26:29]
	global_load_dwordx4 v[42:45], v[10:11], off
	v_lshl_add_u64 v[66:67], v[68:69], 0, v[8:9]
	global_load_dwordx4 v[54:57], v[66:67], off
	v_lshl_add_u64 v[66:67], v[70:71], 0, v[8:9]
	global_load_dwordx4 v[58:61], v[66:67], off
	v_add_u32_e32 v10, s15, v204
	v_ashrrev_i32_e32 v11, 31, v10
	s_waitcnt vmcnt(3)
	v_mfma_f32_16x16x32_bf16 v[30:33], v[50:53], v[46:49], v[30:33]
	v_lshlrev_b64 v[50:51], 6, v[10:11]
	v_lshl_add_u64 v[66:67], s[60:61], 0, v[50:51]
	global_load_dwordx4 v[50:53], v[66:67], off
	v_lshl_add_u64 v[10:11], v[10:11], 2, s[38:39]
	s_waitcnt vmcnt(3)
	v_mfma_f32_16x16x32_bf16 v[26:29], v[42:45], v[46:49], v[26:29]
	s_waitcnt vmcnt(0)
	v_add_f32_e32 v25, v50, v51
	v_mfma_f32_16x16x32_bf16 v[34:37], v[54:57], v[46:49], v[34:37]
	global_load_dwordx4 v[54:57], v[66:67], off offset:16
	global_load_dwordx4 v[62:65], v[66:67], off offset:32
	v_mfma_f32_16x16x32_bf16 v[38:41], v[58:61], v[46:49], v[38:41]
	global_load_dwordx4 v[58:61], v[66:67], off offset:48
	ds_write2_b32 v19, v30, v31 offset1:16
	ds_write2_b32 v19, v32, v33 offset0:32 offset1:48
	s_nop 1
	ds_write2_b32 v22, v34, v35 offset1:16
	ds_write2_b32 v22, v36, v37 offset0:32 offset1:48
	s_nop 0
	ds_write2_b32 v23, v38, v39 offset1:16
	ds_write2_b32 v23, v40, v41 offset0:32 offset1:48
	ds_write2_b32 v24, v26, v27 offset1:16
	ds_write2_b32 v24, v28, v29 offset0:32 offset1:48
	s_waitcnt lgkmcnt(0)
	s_barrier
	v_mov_b32_e32 v34, v100
	v_add_f32_e32 v26, v52, v53
	v_add_f32_e32 v25, v25, v26
	s_waitcnt vmcnt(2)
	v_add_f32_e32 v27, v54, v55
	v_add_f32_e32 v28, v56, v57
	s_waitcnt vmcnt(1)
	v_add_f32_e32 v29, v62, v63
	v_add_f32_e32 v30, v64, v65
	v_add_f32_e32 v26, v27, v28
	s_waitcnt vmcnt(0)
	v_add_f32_e32 v31, v58, v59
	v_add_f32_e32 v32, v60, v61
	v_add_f32_e32 v27, v29, v30
	v_add_f32_e32 v25, v25, v26
	v_add_f32_e32 v28, v31, v32
	v_add_f32_e32 v25, v25, v27
	v_add_f32_e32 v25, v25, v28
	v_fmamk_f32 v25, v25, 0x3a800000, v20
	v_mul_f32_e32 v26, 0x4f800000, v25
	v_cmp_gt_f32_e32 vcc, s57, v25
	s_nop 1
	v_cndmask_b32_e32 v25, v25, v26, vcc
	v_sqrt_f32_e32 v26, v25
	s_nop 0
	v_add_u32_e32 v27, -1, v26
	v_add_u32_e32 v28, 1, v26
	v_fma_f32 v29, -v27, v26, v25
	v_fma_f32 v30, -v28, v26, v25
	v_cmp_ge_f32_e64 s[22:23], 0, v29
	s_nop 1
	v_cndmask_b32_e64 v26, v26, v27, s[22:23]
	v_cmp_lt_f32_e64 s[22:23], 0, v30
	s_nop 1
	v_cndmask_b32_e64 v26, v26, v28, s[22:23]
	v_mul_f32_e32 v27, 0x37800000, v26
	v_cndmask_b32_e32 v26, v26, v27, vcc
	v_cmp_class_f32_e32 vcc, v25, v21
	s_nop 1
	v_cndmask_b32_e32 v25, v26, v25, vcc
	v_div_scale_f32 v35, s[22:23], v25, v25, 1.0
	v_rcp_f32_e32 v37, v35
	ds_read2st64_b32 v[26:27], v12 offset1:16
	ds_read2st64_b32 v[28:29], v12 offset0:32 offset1:48
	ds_read2st64_b32 v[30:31], v12 offset0:64 offset1:80
	ds_read2st64_b32 v[32:33], v12 offset0:96 offset1:112
	v_div_scale_f32 v36, vcc, 1.0, v25, 1.0
	v_fma_f32 v38, -v35, v37, 1.0
	s_waitcnt lgkmcnt(3)
	v_add_f32_e32 v26, 0, v26
	v_fmac_f32_e32 v37, v38, v37
	v_add_f32_e32 v26, v26, v27
	v_mul_f32_e32 v38, v36, v37
	s_waitcnt lgkmcnt(2)
	v_add_f32_e32 v26, v26, v28
	v_fma_f32 v39, -v35, v38, v36
	v_add_f32_e32 v26, v26, v29
	v_fmac_f32_e32 v38, v39, v37
	s_waitcnt lgkmcnt(1)
	v_add_f32_e32 v26, v26, v30
	v_fma_f32 v27, -v35, v38, v36
	v_add_f32_e32 v26, v26, v31
	v_div_fmas_f32 v27, v27, v37, v38
	s_waitcnt lgkmcnt(0)
	v_add_f32_e32 v26, v26, v32
	v_div_fixup_f32 v25, v27, v25, 1.0
	v_add_f32_e32 v26, v26, v33
	s_waitcnt vmcnt(0)
	v_fmac_f32_e32 v34, v25, v26
	v_mul_f32_e64 v26, |v34|, s64
	v_exp_f32_e32 v26, v26
	v_min_f32_e32 v27, 0, v34
	v_lshl_add_u64 v[28:29], v[10:11], 0, s[58:59]
	v_add_f32_e32 v26, 1.0, v26
	v_log_f32_e32 v26, v26
	s_nop 0
	v_fmac_f32_e32 v27, 0xbf317218, v26
	ds_bpermute_b32 v26, v13, v27
	s_waitcnt lgkmcnt(0)
	v_add_f32_e32 v26, v27, v26
	v_cndmask_b32_e64 v26, v26, v27, s[8:9]
	ds_bpermute_b32 v27, v14, v26
	s_waitcnt lgkmcnt(0)
	v_add_f32_e32 v27, v26, v27
	v_cndmask_b32_e64 v26, v27, v26, s[10:11]
	ds_bpermute_b32 v27, v15, v26
	s_waitcnt lgkmcnt(0)
	v_add_f32_e32 v27, v26, v27
	v_cndmask_b32_e64 v26, v27, v26, s[12:13]
	ds_bpermute_b32 v27, v16, v26
	s_waitcnt lgkmcnt(0)
	v_add_f32_e32 v27, v26, v27
	v_cndmask_b32_e64 v26, v27, v26, s[16:17]
	ds_bpermute_b32 v27, v17, v26
	s_waitcnt lgkmcnt(0)
	v_add_f32_e32 v27, v26, v27
	v_cndmask_b32_e64 v27, v27, v26, s[18:19]
	ds_bpermute_b32 v26, v18, v27
	s_waitcnt lgkmcnt(0)
	v_add_f32_e32 v26, v27, v26
	v_cndmask_b32_e64 v27, v26, v27, s[20:21]
	global_store_dword v[28:29], v27, off sc1
	s_and_saveexec_b64 s[22:23], s[0:1]
	s_cbranch_execz .LBB0_445
	s_add_i32 s66, s14, s65
	s_ashr_i32 s67, s66, 31
	s_lshl_b64 s[66:67], s[66:67], 2
	s_add_u32 s66, s74, s66
	s_addc_u32 s67, s75, s67
	global_store_dword v1, v26, s[66:67] sc1
.LBB0_445:
	s_or_b64 exec, exec, s[22:23]
	v_mov_b32_e32 v34, v101
	v_add_u32_e32 v32, 4, v12
	ds_read2st64_b32 v[26:27], v32 offset1:16
	ds_read2st64_b32 v[28:29], v32 offset0:32 offset1:48
	ds_read2st64_b32 v[30:31], v32 offset0:64 offset1:80
	ds_read2st64_b32 v[32:33], v32 offset0:96 offset1:112
	v_lshl_add_u64 v[10:11], v[10:11], 0, s[62:63]
	s_waitcnt lgkmcnt(3)
	v_add_f32_e32 v26, 0, v26
	v_add_f32_e32 v26, v26, v27
	s_waitcnt lgkmcnt(2)
	v_add_f32_e32 v26, v26, v28
	v_add_f32_e32 v26, v26, v29
	s_waitcnt lgkmcnt(1)
	v_add_f32_e32 v26, v26, v30
	v_add_f32_e32 v26, v26, v31
	s_waitcnt lgkmcnt(0)
	v_add_f32_e32 v26, v26, v32
	v_add_f32_e32 v26, v26, v33
	v_fmac_f32_e32 v34, v25, v26
	v_mul_f32_e64 v25, |v34|, s64
	v_exp_f32_e32 v25, v25
	v_min_f32_e32 v26, 0, v34
	v_add_f32_e32 v25, 1.0, v25
	v_log_f32_e32 v25, v25
	s_nop 0
	v_fmac_f32_e32 v26, 0xbf317218, v25
	ds_bpermute_b32 v25, v13, v26
	s_waitcnt lgkmcnt(0)
	v_add_f32_e32 v25, v26, v25
	v_cndmask_b32_e64 v25, v25, v26, s[8:9]
	ds_bpermute_b32 v26, v14, v25
	s_waitcnt lgkmcnt(0)
	v_add_f32_e32 v26, v25, v26
	v_cndmask_b32_e64 v25, v26, v25, s[10:11]
	ds_bpermute_b32 v26, v15, v25
	s_waitcnt lgkmcnt(0)
	v_add_f32_e32 v26, v25, v26
	v_cndmask_b32_e64 v25, v26, v25, s[12:13]
	ds_bpermute_b32 v26, v16, v25
	s_waitcnt lgkmcnt(0)
	v_add_f32_e32 v26, v25, v26
	v_cndmask_b32_e64 v25, v26, v25, s[16:17]
	ds_bpermute_b32 v26, v17, v25
	s_waitcnt lgkmcnt(0)
	v_add_f32_e32 v26, v25, v26
	v_cndmask_b32_e64 v26, v26, v25, s[18:19]
	ds_bpermute_b32 v25, v18, v26
	s_waitcnt lgkmcnt(0)
	v_add_f32_e32 v25, v26, v25
	v_cndmask_b32_e64 v26, v25, v26, s[20:21]
	global_store_dword v[10:11], v26, off sc1
	s_and_saveexec_b64 s[22:23], s[0:1]
	s_cbranch_execz .LBB0_442
	s_add_i32 s33, s14, s65
	s_add_i32 s66, s33, 0x100
	s_ashr_i32 s67, s66, 31
	s_lshl_b64 s[66:67], s[66:67], 2
	s_add_u32 s66, s74, s66
	s_addc_u32 s67, s75, s67
	global_store_dword v1, v25, s[66:67] sc1
	s_branch .LBB0_442
